# hand-written dilated attention: K and V tiles staged row-major by LDS-DMA, V consumed with ds_read_b64_tr_b16 (no LDS transposition pass); plus hand-written cross attention and H2, GEMM unit-start wai
# speedup vs baseline: 1.0145x; 1.0094x over previous
; #define LAS __attribute__((address_space(3)))
; #define DSEC(k) do { if (PROBE_DSEC) { const unsigned long long tn_ = __builtin_amdgcn_s_memrealtime(); if (PROBE_DSEC == (k)) tsec += tn_ - tl_; tl_ = tn_; } } while (0)
; DI void dil_attn_phase(LAS unsigned char* L, const bf16* Z, const float* cosT, const float* sinT, bf16* OG, float* LSE, int G, int bid, int tid, unsigned long long& tsec) {
;     ...
;     if (bid < 1536) DIL_LOAD(bid);
;     for (int unit = bid; unit < 1536; unit += G) {
;         const int j = unit & 31, h = (unit >> 5) & 3, gb = unit >> 7, g = gb % 3, b = gb / 3;
;         const int dsh = 2 * g, Lseg = T >> dsh;
;         const int p0 = 128 * j, r = p0 / Lseg, u0 = p0 & (Lseg - 1);
;         const int tokbase = b * T + r;
;         const int colq = g * 512 + h * 128;
;         asm volatile("" : "+v"(kreg[0]), "+v"(kreg[1]), "+v"(kreg[2]), "+v"(kreg[3]), "+v"(kreg[4]), "+v"(kreg[5]), "+v"(kreg[6]), "+v"(kreg[7]));
;         asm volatile("" : "+v"(vreg[0]), "+v"(vreg[1]), "+v"(vreg[2]), "+v"(vreg[3]), "+v"(vreg[4]), "+v"(vreg[5]), "+v"(vreg[6]), "+v"(vreg[7]));
;         const int qi = 16 * wid + fr; const size_t tq = (size_t)(tokbase + ((u0 + qi) << dsh));
;         bf16x8 qf[4];
; #pragma unroll
;         for (int k4 = 0; k4 < 4; ++k4) qf[k4] = *(const bf16x8*)(Z + tq * NATT + colq + 32 * k4 + 8 * fq);
;         __syncthreads();
;         DSEC(6);
; #pragma unroll
;         for (int i = 0; i < 8; ++i) {
;             const int p = tid + 512 * i, kk = p >> 4, cb = p & 15; const bool ok = u0 - 128 + kk >= 0;
;             const u32x4 zz = (u32x4){0u, 0u, 0u, 0u}; const u32x4 kx = ok ? kreg[i] : zz, x = ok ? vreg[i] : zz;
;             *(LAS u32x4*)(KL + kk * KSTR + 16 * cb) = kx;
;             const unsigned base = (unsigned)((((kk >> 2) ^ (cb & 7)) << 3) + (kk & 3) * 2);
; #pragma unroll
;             for (int jj = 0; jj < 8; ++jj) *(LAS unsigned short*)(VL + (8 * cb + jj) * VSTR + base) = (unsigned short)(x[jj >> 1] >> (16 * (jj & 1)));
;         }
;         DSEC(1);
;         { const int nu = unit + G < 1536 ? unit + G : unit; DIL_LOAD(nu); }
.LBB0_385:
	s_cmpk_gt_i32 s28, 0x5ff
	v_readfirstlane_b32 s2, v71
	s_cbranch_scc1 .LBB0_391
	s_lshr_b32 s3, s2, 6
	s_lshl_b32 s40, s3, 13
	s_mov_b32 s48, 0x3f317217
	s_add_u32 s34, s78, 0x6400000
	s_addc_u32 s35, s79, 0
	s_add_u32 s36, s78, 0xf400000
	s_addc_u32 s37, s79, 0
	s_add_u32 s38, s78, 0x14600000
	s_addc_u32 s39, s79, 0
	v_and_b32_e32 v186, 63, v71
	v_and_b32_e32 v187, 15, v186
	v_lshrrev_b32_e32 v188, 4, v186
	v_lshl_add_u32 v189, s3, 4, v187
	s_and_b32 s4, s3, 6
	v_lshlrev_b32_e32 v190, 2, v188
	v_lshl_add_u32 v190, s4, 4, v190
	v_xor_b32_e32 v191, 16, v186
	v_lshlrev_b32_e32 v191, 2, v191
	v_xor_b32_e32 v192, 32, v186
	v_lshlrev_b32_e32 v192, 2, v192
	v_lshl_add_u32 v193, s3, 5, v188
	v_mov_b32_e32 v217, 0xff800000
	v_add_u32_e32 v218, 0, v188
	v_xor_b32_e32 v218, v218, v187
	v_lshlrev_b32_e32 v198, 4, v218
	v_lshlrev_b32_e32 v218, 2, v188
	v_or_b32_e32 v218, 0, v218
	v_xor_b32_e32 v218, v218, v187
	v_lshlrev_b32_e32 v206, 4, v218
	v_add_u32_e32 v218, 4, v188
	v_xor_b32_e32 v218, v218, v187
	v_lshlrev_b32_e32 v199, 4, v218
	v_lshlrev_b32_e32 v218, 2, v188
	v_or_b32_e32 v218, 1, v218
	v_xor_b32_e32 v218, v218, v187
	v_lshlrev_b32_e32 v207, 4, v218
	v_add_u32_e32 v218, 8, v188
	v_xor_b32_e32 v218, v218, v187
	v_lshlrev_b32_e32 v200, 4, v218
	v_lshlrev_b32_e32 v218, 2, v188
	v_or_b32_e32 v218, 2, v218
	v_xor_b32_e32 v218, v218, v187
	v_lshlrev_b32_e32 v208, 4, v218
	v_add_u32_e32 v218, 12, v188
	v_xor_b32_e32 v218, v218, v187
	v_lshlrev_b32_e32 v201, 4, v218
	v_lshlrev_b32_e32 v218, 2, v188
	v_or_b32_e32 v218, 3, v218
	v_xor_b32_e32 v218, v218, v187
	v_lshlrev_b32_e32 v209, 4, v218
	v_lshl_add_u32 v219, s4, 4, v187
	v_lshlrev_b32_e32 v219, 8, v219
	v_add_u32_e32 v218, 0, v188
	v_xor_b32_e32 v218, v218, v187
	v_lshl_add_u32 v174, v218, 4, v219
	v_add_u32_e32 v218, 4, v188
	v_xor_b32_e32 v218, v218, v187
	v_lshl_add_u32 v175, v218, 4, v219
	v_add_u32_e32 v218, 8, v188
	v_xor_b32_e32 v218, v218, v187
	v_lshl_add_u32 v176, v218, 4, v219
	v_add_u32_e32 v218, 12, v188
	v_xor_b32_e32 v218, v218, v187
	v_lshl_add_u32 v177, v218, 4, v219
	v_lshrrev_b32_e32 v220, 2, v187
	v_lshl_add_u32 v219, v188, 2, v220
	v_lshl_add_u32 v219, s4, 4, v219
	v_lshlrev_b32_e32 v219, 8, v219
	v_lshl_or_b32 v221, v220, 2, v188
	v_bfe_u32 v222, v187, 1, 1
	v_and_b32_e32 v223, 1, v187
	v_lshl_add_u32 v219, v223, 3, v219
	v_add_u32_e32 v219, 0x10000, v219
	v_or_b32_e32 v218, 0, v222
	v_xor_b32_e32 v218, v218, v221
	v_lshl_add_u32 v178, v218, 4, v219
	v_or_b32_e32 v218, 2, v222
	v_xor_b32_e32 v218, v218, v221
	v_lshl_add_u32 v179, v218, 4, v219
	v_or_b32_e32 v218, 4, v222
	v_xor_b32_e32 v218, v218, v221
	v_lshl_add_u32 v180, v218, 4, v219
	v_or_b32_e32 v218, 6, v222
	v_xor_b32_e32 v218, v218, v221
	v_lshl_add_u32 v181, v218, 4, v219
	v_or_b32_e32 v218, 8, v222
	v_xor_b32_e32 v218, v218, v221
	v_lshl_add_u32 v182, v218, 4, v219
	v_or_b32_e32 v218, 10, v222
	v_xor_b32_e32 v218, v218, v221
	v_lshl_add_u32 v183, v218, 4, v219
	v_or_b32_e32 v218, 12, v222
	v_xor_b32_e32 v218, v218, v221
	v_lshl_add_u32 v184, v218, 4, v219
	v_or_b32_e32 v218, 14, v222
	v_xor_b32_e32 v218, v218, v221
	v_lshl_add_u32 v185, v218, 4, v219
	s_mov_b32 s5, s28
	s_and_b32 s41, s5, 31
	s_bfe_u32 s42, s5, 0x20005
	s_lshr_b32 s43, s5, 7
	s_mul_i32 s23, s43, 11
	s_lshr_b32 s23, s23, 5
	s_mul_i32 s25, s23, 3
	s_sub_u32 s25, s43, s25
	s_lshl_b32 s50, s25, 1
	s_lshl_b32 s26, s41, 7
	s_sub_u32 s27, 12, s50
	s_lshr_b32 s27, s26, s27
	s_lshr_b32 s51, 0xfff, s50
	s_and_b32 s51, s26, s51
	s_lshl_b32 s23, s23, 12
	s_add_u32 s23, s23, s27
	s_lshl_b32 s26, s25, 10
	s_lshl_b32 s27, s42, 8
	s_add_u32 s26, s26, s27
	s_mul_i32 s27, s23, 0x2400
	s_add_u32 s27, s27, s26
	s_add_u32 s52, s34, s27
	s_addc_u32 s53, s35, 0
	s_mov_b32 s18, s50
	s_mov_b32 s19, s51
	s_mul_i32 s27, s23, 0xc00
	s_add_u32 s27, s27, s26
	s_add_u32 s14, s36, s27
	s_addc_u32 s15, s37, 0
	s_mul_i32 s27, s23, 48
	s_lshl_b32 s26, s25, 4
	s_lshl_b32 s23, s42, 2
	s_add_u32 s26, s26, s23
	s_add_u32 s27, s27, s26
	s_add_u32 s16, s38, s27
	s_addc_u32 s17, s39, 0
	v_add_u32_e32 v218, s19, v189
	v_lshlrev_b32_e32 v218, s18, v218
	v_mul_u32_u24_e32 v219, 3, v218
	v_lshlrev_b32_e32 v219, 10, v219
	v_lshl_add_u32 v213, v188, 3, v219
	v_mul_u32_u24_e32 v214, 48, v218
	s_cmp_eq_u32 s19, 0
	s_cselect_b32 s23, 0x80, 0
	v_max_u32_e32 v219, s23, v189
	v_sub_u32_e32 v215, v190, v219
	v_sub_u32_e32 v216, v189, v219
	v_add_u32_e32 v216, 0x80, v216
	v_add_u32_e32 v218, s51, v189
	v_lshlrev_b32_e32 v218, s50, v218
	v_mul_u32_u24_e32 v218, 9, v218
	v_lshlrev_b32_e32 v218, 10, v218
	v_lshl_add_u32 v212, v188, 4, v218
	s_add_u32 s44, s52, 3072
	s_addc_u32 s45, s53, 0
	s_sub_u32 s23, s51, 0x80
	v_add_u32_e32 v218, 0, v193
	v_add_u32_e32 v218, s23, v218
	v_max_i32_e32 v218, 0, v218
	v_lshlrev_b32_e32 v218, s50, v218
	v_mul_u32_u24_e32 v218, 9, v218
	v_lshl_add_u32 v218, v218, 10, v198
	s_add_u32 m0, s40, 0
	s_nop 0
	global_load_lds_dwordx4 v218, s[44:45]
	v_add_u32_e32 v218, 4, v193
	v_add_u32_e32 v218, s23, v218
	v_max_i32_e32 v218, 0, v218
	v_lshlrev_b32_e32 v218, s50, v218
	v_mul_u32_u24_e32 v218, 9, v218
	v_lshl_add_u32 v218, v218, 10, v199
	s_add_u32 m0, s40, 1024
	s_nop 0
	global_load_lds_dwordx4 v218, s[44:45]
	v_add_u32_e32 v218, 8, v193
	v_add_u32_e32 v218, s23, v218
	v_max_i32_e32 v218, 0, v218
	v_lshlrev_b32_e32 v218, s50, v218
	v_mul_u32_u24_e32 v218, 9, v218
	v_lshl_add_u32 v218, v218, 10, v200
	s_add_u32 m0, s40, 2048
	s_nop 0
	global_load_lds_dwordx4 v218, s[44:45]
	v_add_u32_e32 v218, 12, v193
	v_add_u32_e32 v218, s23, v218
	v_max_i32_e32 v218, 0, v218
	v_lshlrev_b32_e32 v218, s50, v218
	v_mul_u32_u24_e32 v218, 9, v218
	v_lshl_add_u32 v218, v218, 10, v201
; #define LAS __attribute__((address_space(3)))
; #define MFMA16(a, b, c) __builtin_amdgcn_mfma_f32_16x16x32_bf16((a), (b), (c), 0, 0, 0)
; #define DSEC(k) do { if (PROBE_DSEC) { const unsigned long long tn_ = __builtin_amdgcn_s_memrealtime(); if (PROBE_DSEC == (k)) tsec += tn_ - tl_; tl_ = tn_; } } while (0)
; DI void dil_attn_phase(LAS unsigned char* L, const bf16* Z, const float* cosT, const float* sinT, bf16* OG, float* LSE, int G, int bid, int tid, unsigned long long& tsec) {
;     ...
;         const int qi = 16 * wid + fr; const size_t tq = (size_t)(tokbase + ((u0 + qi) << dsh));
;         bf16x8 qf[4];
; #pragma unroll
;         for (int k4 = 0; k4 < 4; ++k4) qf[k4] = *(const bf16x8*)(Z + tq * NATT + colq + 32 * k4 + 8 * fq);
;         __syncthreads();
;         DSEC(6);
; #pragma unroll
;         for (int i = 0; i < 8; ++i) {
;             const int p = tid + 512 * i, kk = p >> 4, cb = p & 15; const bool ok = u0 - 128 + kk >= 0;
;             const u32x4 zz = (u32x4){0u, 0u, 0u, 0u}; const u32x4 kx = ok ? kreg[i] : zz, x = ok ? vreg[i] : zz;
;             *(LAS u32x4*)(KL + kk * KSTR + 16 * cb) = kx;
;             const unsigned base = (unsigned)((((kk >> 2) ^ (cb & 7)) << 3) + (kk & 3) * 2);
; #pragma unroll
;             for (int jj = 0; jj < 8; ++jj) *(LAS unsigned short*)(VL + (8 * cb + jj) * VSTR + base) = (unsigned short)(x[jj >> 1] >> (16 * (jj & 1)));
;         }
;         DSEC(1);
;         { const int nu = unit + G < 1536 ? unit + G : unit; DIL_LOAD(nu); }
;         DSEC(2);
;         __syncthreads();
;         DSEC(3);
;         const int tw = wid & ~1;
;         f32x4 s[10];
; #pragma unroll
;         for (int tix = 0; tix < 10; ++tix) s[tix] = (f32x4){0.f, 0.f, 0.f, 0.f};
; #pragma unroll
;         for (int k4 = 0; k4 < 4; ++k4)
; #pragma unroll
;             for (int t5 = 0; t5 < 2; ++t5) { bf16x8 av[5];
; #pragma unroll
;                 for (int tix = 0; tix < 5; ++tix) av[tix] = *(const LAS bf16x8*)(KL + (16 * (tw + 5 * t5 + tix) + fr) * KSTR + (32 * k4 + 8 * fq) * 2);
; #pragma unroll
;                 for (int tix = 0; tix < 5; ++tix) s[5 * t5 + tix] = MFMA16(av[tix], qf[k4], s[5 * t5 + tix]); }
	s_add_u32 m0, s40, 3072
	s_nop 0
	global_load_lds_dwordx4 v218, s[44:45]
	v_add_u32_e32 v218, 16, v193
	v_add_u32_e32 v218, s23, v218
	v_max_i32_e32 v218, 0, v218
	v_lshlrev_b32_e32 v218, s50, v218
	v_mul_u32_u24_e32 v218, 9, v218
	v_lshl_add_u32 v218, v218, 10, v198
	s_add_u32 m0, s40, 4096
	s_nop 0
	global_load_lds_dwordx4 v218, s[44:45]
	v_add_u32_e32 v218, 20, v193
	v_add_u32_e32 v218, s23, v218
	v_max_i32_e32 v218, 0, v218
	v_lshlrev_b32_e32 v218, s50, v218
	v_mul_u32_u24_e32 v218, 9, v218
	v_lshl_add_u32 v218, v218, 10, v199
	s_add_u32 m0, s40, 5120
	s_nop 0
	global_load_lds_dwordx4 v218, s[44:45]
	v_add_u32_e32 v218, 24, v193
	v_add_u32_e32 v218, s23, v218
	v_max_i32_e32 v218, 0, v218
	v_lshlrev_b32_e32 v218, s50, v218
	v_mul_u32_u24_e32 v218, 9, v218
	v_lshl_add_u32 v218, v218, 10, v200
	s_add_u32 m0, s40, 6144
	s_nop 0
	global_load_lds_dwordx4 v218, s[44:45]
	v_add_u32_e32 v218, 28, v193
	v_add_u32_e32 v218, s23, v218
	v_max_i32_e32 v218, 0, v218
	v_lshlrev_b32_e32 v218, s50, v218
	v_mul_u32_u24_e32 v218, 9, v218
	v_lshl_add_u32 v218, v218, 10, v201
	s_add_u32 m0, s40, 7168
	s_nop 0
	global_load_lds_dwordx4 v218, s[44:45]
	global_load_dwordx4 v[42:45], v212, s[52:53]
	global_load_dwordx4 v[46:49], v212, s[52:53] offset:64
	global_load_dwordx4 v[50:53], v212, s[52:53] offset:128
	global_load_dwordx4 v[54:57], v212, s[52:53] offset:192
	s_add_u32 s44, s52, 6144
	s_addc_u32 s45, s53, 0
	s_sub_u32 s23, s51, 0x80
	v_add_u32_e32 v218, 0, v193
	v_add_u32_e32 v218, s23, v218
	v_max_i32_e32 v218, 0, v218
	v_lshlrev_b32_e32 v218, s50, v218
	v_mul_u32_u24_e32 v218, 9, v218
	v_lshl_add_u32 v218, v218, 10, v206
	s_add_u32 m0, s40, 65536
	s_nop 0
	global_load_lds_dwordx4 v218, s[44:45]
	v_add_u32_e32 v218, 4, v193
	v_add_u32_e32 v218, s23, v218
	v_max_i32_e32 v218, 0, v218
	v_lshlrev_b32_e32 v218, s50, v218
	v_mul_u32_u24_e32 v218, 9, v218
	v_lshl_add_u32 v218, v218, 10, v207
	s_add_u32 m0, s40, 66560
	s_nop 0
	global_load_lds_dwordx4 v218, s[44:45]
	v_add_u32_e32 v218, 8, v193
	v_add_u32_e32 v218, s23, v218
	v_max_i32_e32 v218, 0, v218
	v_lshlrev_b32_e32 v218, s50, v218
	v_mul_u32_u24_e32 v218, 9, v218
	v_lshl_add_u32 v218, v218, 10, v208
	s_add_u32 m0, s40, 67584
	s_nop 0
	global_load_lds_dwordx4 v218, s[44:45]
	v_add_u32_e32 v218, 12, v193
	v_add_u32_e32 v218, s23, v218
	v_max_i32_e32 v218, 0, v218
	v_lshlrev_b32_e32 v218, s50, v218
	v_mul_u32_u24_e32 v218, 9, v218
	v_lshl_add_u32 v218, v218, 10, v209
	s_add_u32 m0, s40, 68608
	s_nop 0
	global_load_lds_dwordx4 v218, s[44:45]
	v_add_u32_e32 v218, 16, v193
	v_add_u32_e32 v218, s23, v218
	v_max_i32_e32 v218, 0, v218
	v_lshlrev_b32_e32 v218, s50, v218
	v_mul_u32_u24_e32 v218, 9, v218
	v_lshl_add_u32 v218, v218, 10, v206
	s_add_u32 m0, s40, 69632
	s_nop 0
	global_load_lds_dwordx4 v218, s[44:45]
	v_add_u32_e32 v218, 20, v193
	v_add_u32_e32 v218, s23, v218
	v_max_i32_e32 v218, 0, v218
	v_lshlrev_b32_e32 v218, s50, v218
	v_mul_u32_u24_e32 v218, 9, v218
	v_lshl_add_u32 v218, v218, 10, v207
	s_add_u32 m0, s40, 70656
	s_nop 0
	global_load_lds_dwordx4 v218, s[44:45]
	v_add_u32_e32 v218, 24, v193
	v_add_u32_e32 v218, s23, v218
	v_max_i32_e32 v218, 0, v218
	v_lshlrev_b32_e32 v218, s50, v218
	v_mul_u32_u24_e32 v218, 9, v218
	v_lshl_add_u32 v218, v218, 10, v208
	s_add_u32 m0, s40, 71680
	s_nop 0
	global_load_lds_dwordx4 v218, s[44:45]
	v_add_u32_e32 v218, 28, v193
	v_add_u32_e32 v218, s23, v218
	v_max_i32_e32 v218, 0, v218
	v_lshlrev_b32_e32 v218, s50, v218
	v_mul_u32_u24_e32 v218, 9, v218
	v_lshl_add_u32 v218, v218, 10, v209
	s_add_u32 m0, s40, 72704
	s_nop 0
	global_load_lds_dwordx4 v218, s[44:45]
	s_waitcnt vmcnt(8)
	s_barrier
.Lda_loop:
	ds_read_b128 v[58:61], v174 offset:0
	ds_read_b128 v[62:65], v174 offset:4096
	ds_read_b128 v[66:69], v174 offset:8192
	ds_read_b128 v[70:73], v174 offset:12288
	ds_read_b128 v[74:77], v174 offset:16384
	ds_read_b128 v[90:93], v174 offset:20480
	ds_read_b128 v[94:97], v174 offset:24576
	ds_read_b128 v[98:101], v174 offset:28672
	ds_read_b128 v[102:105], v174 offset:32768
	ds_read_b128 v[106:109], v174 offset:36864
	s_waitcnt lgkmcnt(5)
	v_mfma_f32_16x16x32_bf16 v[2:5], v[58:61], v[42:45], 0
	ds_read_b128 v[58:61], v175 offset:0
	v_mfma_f32_16x16x32_bf16 v[6:9], v[62:65], v[42:45], 0
	ds_read_b128 v[62:65], v175 offset:4096
	v_mfma_f32_16x16x32_bf16 v[10:13], v[66:69], v[42:45], 0
	ds_read_b128 v[66:69], v175 offset:8192
	v_mfma_f32_16x16x32_bf16 v[14:17], v[70:73], v[42:45], 0
	ds_read_b128 v[70:73], v175 offset:12288
	v_mfma_f32_16x16x32_bf16 v[18:21], v[74:77], v[42:45], 0
	ds_read_b128 v[74:77], v175 offset:16384
	s_waitcnt lgkmcnt(5)
	v_mfma_f32_16x16x32_bf16 v[22:25], v[90:93], v[42:45], 0
	ds_read_b128 v[90:93], v175 offset:20480
	v_mfma_f32_16x16x32_bf16 v[26:29], v[94:97], v[42:45], 0
	ds_read_b128 v[94:97], v175 offset:24576
	v_mfma_f32_16x16x32_bf16 v[30:33], v[98:101], v[42:45], 0
	ds_read_b128 v[98:101], v175 offset:28672
	v_mfma_f32_16x16x32_bf16 v[34:37], v[102:105], v[42:45], 0
	ds_read_b128 v[102:105], v175 offset:32768
	v_mfma_f32_16x16x32_bf16 v[38:41], v[106:109], v[42:45], 0
	ds_read_b128 v[106:109], v175 offset:36864
	s_waitcnt lgkmcnt(5)
	v_mfma_f32_16x16x32_bf16 v[2:5], v[58:61], v[46:49], v[2:5]
	ds_read_b128 v[58:61], v176 offset:0
	v_mfma_f32_16x16x32_bf16 v[6:9], v[62:65], v[46:49], v[6:9]
	ds_read_b128 v[62:65], v176 offset:4096
	v_mfma_f32_16x16x32_bf16 v[10:13], v[66:69], v[46:49], v[10:13]
	ds_read_b128 v[66:69], v176 offset:8192
	v_mfma_f32_16x16x32_bf16 v[14:17], v[70:73], v[46:49], v[14:17]
	ds_read_b128 v[70:73], v176 offset:12288
	v_mfma_f32_16x16x32_bf16 v[18:21], v[74:77], v[46:49], v[18:21]
	ds_read_b128 v[74:77], v176 offset:16384
	s_waitcnt lgkmcnt(5)
; #define LAS __attribute__((address_space(3)))
; #define MFMA16(a, b, c) __builtin_amdgcn_mfma_f32_16x16x32_bf16((a), (b), (c), 0, 0, 0)
; #define DSEC(k) do { if (PROBE_DSEC) { const unsigned long long tn_ = __builtin_amdgcn_s_memrealtime(); if (PROBE_DSEC == (k)) tsec += tn_ - tl_; tl_ = tn_; } } while (0)
; DI void dil_attn_phase(LAS unsigned char* L, const bf16* Z, const float* cosT, const float* sinT, bf16* OG, float* LSE, int G, int bid, int tid, unsigned long long& tsec) {
;     ...
;         { const int nu = unit + G < 1536 ? unit + G : unit; DIL_LOAD(nu); }
;     ...
;         for (int k4 = 0; k4 < 4; ++k4)
; #pragma unroll
;             for (int t5 = 0; t5 < 2; ++t5) { bf16x8 av[5];
; #pragma unroll
;                 for (int tix = 0; tix < 5; ++tix) av[tix] = *(const LAS bf16x8*)(KL + (16 * (tw + 5 * t5 + tix) + fr) * KSTR + (32 * k4 + 8 * fq) * 2);
; #pragma unroll
;                 for (int tix = 0; tix < 5; ++tix) s[5 * t5 + tix] = MFMA16(av[tix], qf[k4], s[5 * t5 + tix]); }
;         DSEC(4);
;         const float scale = 0.08838834764831845f; float mx = -INFINITY;
; #pragma unroll
;         for (int tix = 0; tix < 10; ++tix)
; #pragma unroll
;             for (int e = 0; e < 4; ++e) { const int kk = 16 * (tw + tix) + 4 * fq + e; const bool ok = (kk >= qi) && (kk <= qi + 128) && (u0 - 128 + kk >= 0);
;                 const float v = ok ? s[tix][e] * scale : -INFINITY; s[tix][e] = v; mx = fmaxf(mx, v); }
	v_mfma_f32_16x16x32_bf16 v[22:25], v[90:93], v[46:49], v[22:25]
	ds_read_b128 v[90:93], v176 offset:20480
	v_mfma_f32_16x16x32_bf16 v[26:29], v[94:97], v[46:49], v[26:29]
	ds_read_b128 v[94:97], v176 offset:24576
	v_mfma_f32_16x16x32_bf16 v[30:33], v[98:101], v[46:49], v[30:33]
	ds_read_b128 v[98:101], v176 offset:28672
	v_mfma_f32_16x16x32_bf16 v[34:37], v[102:105], v[46:49], v[34:37]
	ds_read_b128 v[102:105], v176 offset:32768
	v_mfma_f32_16x16x32_bf16 v[38:41], v[106:109], v[46:49], v[38:41]
	ds_read_b128 v[106:109], v176 offset:36864
	s_waitcnt lgkmcnt(5)
	v_mfma_f32_16x16x32_bf16 v[2:5], v[58:61], v[50:53], v[2:5]
	ds_read_b128 v[58:61], v177 offset:0
	v_mfma_f32_16x16x32_bf16 v[6:9], v[62:65], v[50:53], v[6:9]
	ds_read_b128 v[62:65], v177 offset:4096
	v_mfma_f32_16x16x32_bf16 v[10:13], v[66:69], v[50:53], v[10:13]
	ds_read_b128 v[66:69], v177 offset:8192
	v_mfma_f32_16x16x32_bf16 v[14:17], v[70:73], v[50:53], v[14:17]
	ds_read_b128 v[70:73], v177 offset:12288
	v_mfma_f32_16x16x32_bf16 v[18:21], v[74:77], v[50:53], v[18:21]
	ds_read_b128 v[74:77], v177 offset:16384
	s_waitcnt lgkmcnt(5)
	v_mfma_f32_16x16x32_bf16 v[22:25], v[90:93], v[50:53], v[22:25]
	ds_read_b128 v[90:93], v177 offset:20480
	v_mfma_f32_16x16x32_bf16 v[26:29], v[94:97], v[50:53], v[26:29]
	ds_read_b128 v[94:97], v177 offset:24576
	v_mfma_f32_16x16x32_bf16 v[30:33], v[98:101], v[50:53], v[30:33]
	ds_read_b128 v[98:101], v177 offset:28672
	v_mfma_f32_16x16x32_bf16 v[34:37], v[102:105], v[50:53], v[34:37]
	ds_read_b128 v[102:105], v177 offset:32768
	v_mfma_f32_16x16x32_bf16 v[38:41], v[106:109], v[50:53], v[38:41]
	ds_read_b128 v[106:109], v177 offset:36864
	s_waitcnt lgkmcnt(5)
	v_mfma_f32_16x16x32_bf16 v[2:5], v[58:61], v[54:57], v[2:5]
	v_mfma_f32_16x16x32_bf16 v[6:9], v[62:65], v[54:57], v[6:9]
	v_mfma_f32_16x16x32_bf16 v[10:13], v[66:69], v[54:57], v[10:13]
	v_mfma_f32_16x16x32_bf16 v[14:17], v[70:73], v[54:57], v[14:17]
	v_mfma_f32_16x16x32_bf16 v[18:21], v[74:77], v[54:57], v[18:21]
	s_waitcnt lgkmcnt(0)
	v_mfma_f32_16x16x32_bf16 v[22:25], v[90:93], v[54:57], v[22:25]
	v_mfma_f32_16x16x32_bf16 v[26:29], v[94:97], v[54:57], v[26:29]
	v_mfma_f32_16x16x32_bf16 v[30:33], v[98:101], v[54:57], v[30:33]
	v_mfma_f32_16x16x32_bf16 v[34:37], v[102:105], v[54:57], v[34:37]
	v_mfma_f32_16x16x32_bf16 v[38:41], v[106:109], v[54:57], v[38:41]
	s_barrier
	s_add_u32 s6, s5, s22
	s_cmp_lt_u32 s6, 0x600
	s_cselect_b32 s6, s6, s5
	s_and_b32 s41, s6, 31
	s_bfe_u32 s42, s6, 0x20005
	s_lshr_b32 s43, s6, 7
	s_mul_i32 s23, s43, 11
	s_lshr_b32 s23, s23, 5
	s_mul_i32 s25, s23, 3
	s_sub_u32 s25, s43, s25
	s_lshl_b32 s50, s25, 1
	s_lshl_b32 s26, s41, 7
	s_sub_u32 s27, 12, s50
	s_lshr_b32 s27, s26, s27
	s_lshr_b32 s51, 0xfff, s50
	s_and_b32 s51, s26, s51
	s_lshl_b32 s23, s23, 12
	s_add_u32 s23, s23, s27
	s_lshl_b32 s26, s25, 10
	s_lshl_b32 s27, s42, 8
	s_add_u32 s26, s26, s27
	s_mul_i32 s27, s23, 0x2400
	s_add_u32 s27, s27, s26
	s_add_u32 s52, s34, s27
	s_addc_u32 s53, s35, 0
	v_add_u32_e32 v218, s51, v189
	v_lshlrev_b32_e32 v218, s50, v218
	v_mul_u32_u24_e32 v218, 9, v218
	v_lshlrev_b32_e32 v218, 10, v218
	v_lshl_add_u32 v212, v188, 4, v218
	s_add_u32 s44, s52, 3072
	s_addc_u32 s45, s53, 0
	s_sub_u32 s23, s51, 0x80
	v_add_u32_e32 v218, 0, v193
	v_add_u32_e32 v218, s23, v218
	v_max_i32_e32 v218, 0, v218
	v_lshlrev_b32_e32 v218, s50, v218
	v_mul_u32_u24_e32 v218, 9, v218
	v_lshl_add_u32 v218, v218, 10, v198
	s_add_u32 m0, s40, 0
	s_nop 0
	global_load_lds_dwordx4 v218, s[44:45]
	v_add_u32_e32 v218, 4, v193
	v_add_u32_e32 v218, s23, v218
	v_max_i32_e32 v218, 0, v218
	v_lshlrev_b32_e32 v218, s50, v218
	v_mul_u32_u24_e32 v218, 9, v218
	v_lshl_add_u32 v218, v218, 10, v199
	s_add_u32 m0, s40, 1024
	s_nop 0
	global_load_lds_dwordx4 v218, s[44:45]
	v_add_u32_e32 v218, 8, v193
	v_add_u32_e32 v218, s23, v218
	v_max_i32_e32 v218, 0, v218
	v_lshlrev_b32_e32 v218, s50, v218
	v_mul_u32_u24_e32 v218, 9, v218
	v_lshl_add_u32 v218, v218, 10, v200
	s_add_u32 m0, s40, 2048
	s_nop 0
	global_load_lds_dwordx4 v218, s[44:45]
	v_add_u32_e32 v218, 12, v193
	v_add_u32_e32 v218, s23, v218
	v_max_i32_e32 v218, 0, v218
	v_lshlrev_b32_e32 v218, s50, v218
	v_mul_u32_u24_e32 v218, 9, v218
	v_lshl_add_u32 v218, v218, 10, v201
	s_add_u32 m0, s40, 3072
	s_nop 0
	global_load_lds_dwordx4 v218, s[44:45]
	v_add_u32_e32 v218, 16, v193
	v_add_u32_e32 v218, s23, v218
	v_max_i32_e32 v218, 0, v218
	v_lshlrev_b32_e32 v218, s50, v218
	v_mul_u32_u24_e32 v218, 9, v218
	v_lshl_add_u32 v218, v218, 10, v198
	s_add_u32 m0, s40, 4096
	s_nop 0
	global_load_lds_dwordx4 v218, s[44:45]
	v_add_u32_e32 v218, 20, v193
	v_add_u32_e32 v218, s23, v218
	v_max_i32_e32 v218, 0, v218
	v_lshlrev_b32_e32 v218, s50, v218
	v_mul_u32_u24_e32 v218, 9, v218
	v_lshl_add_u32 v218, v218, 10, v199
	s_add_u32 m0, s40, 5120
	s_nop 0
	global_load_lds_dwordx4 v218, s[44:45]
	v_add_u32_e32 v218, 24, v193
	v_add_u32_e32 v218, s23, v218
	v_max_i32_e32 v218, 0, v218
	v_lshlrev_b32_e32 v218, s50, v218
	v_mul_u32_u24_e32 v218, 9, v218
	v_lshl_add_u32 v218, v218, 10, v200
	s_add_u32 m0, s40, 6144
	s_nop 0
	global_load_lds_dwordx4 v218, s[44:45]
	v_add_u32_e32 v218, 28, v193
	v_add_u32_e32 v218, s23, v218
	v_max_i32_e32 v218, 0, v218
	v_lshlrev_b32_e32 v218, s50, v218
	v_mul_u32_u24_e32 v218, 9, v218
	v_lshl_add_u32 v218, v218, 10, v201
	s_add_u32 m0, s40, 7168
	s_nop 0
	global_load_lds_dwordx4 v218, s[44:45]
	global_load_dwordx4 v[42:45], v212, s[52:53]
	global_load_dwordx4 v[46:49], v212, s[52:53] offset:64
	global_load_dwordx4 v[50:53], v212, s[52:53] offset:128
	global_load_dwordx4 v[54:57], v212, s[52:53] offset:192
	v_mul_f32_e32 v2, 0x3db504f3, v2
	v_add_u32_e32 v218, 0, v215
; DI void dil_attn_phase(LAS unsigned char* L, const bf16* Z, const float* cosT, const float* sinT, bf16* OG, float* LSE, int G, int bid, int tid, unsigned long long& tsec) {
;     ...
;         const float scale = 0.08838834764831845f; float mx = -INFINITY;
; #pragma unroll
;         for (int tix = 0; tix < 10; ++tix)
; #pragma unroll
;             for (int e = 0; e < 4; ++e) { const int kk = 16 * (tw + tix) + 4 * fq + e; const bool ok = (kk >= qi) && (kk <= qi + 128) && (u0 - 128 + kk >= 0);
;                 const float v = ok ? s[tix][e] * scale : -INFINITY; s[tix][e] = v; mx = fmaxf(mx, v); }
;         mx = fmaxf(mx, __shfl_xor(mx, 16)); mx = fmaxf(mx, __shfl_xor(mx, 32));
	v_cmp_ge_u32_e32 vcc, v216, v218
	v_cndmask_b32_e32 v2, v217, v2, vcc
	v_mul_f32_e32 v3, 0x3db504f3, v3
	v_add_u32_e32 v218, 1, v215
	v_cmp_ge_u32_e32 vcc, v216, v218
	v_cndmask_b32_e32 v3, v217, v3, vcc
	v_mul_f32_e32 v4, 0x3db504f3, v4
	v_add_u32_e32 v218, 2, v215
	v_cmp_ge_u32_e32 vcc, v216, v218
	v_cndmask_b32_e32 v4, v217, v4, vcc
	v_mul_f32_e32 v5, 0x3db504f3, v5
	v_add_u32_e32 v218, 3, v215
	v_cmp_ge_u32_e32 vcc, v216, v218
	v_cndmask_b32_e32 v5, v217, v5, vcc
	v_mul_f32_e32 v6, 0x3db504f3, v6
	v_add_u32_e32 v218, 16, v215
	v_cmp_ge_u32_e32 vcc, v216, v218
	v_cndmask_b32_e32 v6, v217, v6, vcc
	v_mul_f32_e32 v7, 0x3db504f3, v7
	v_add_u32_e32 v218, 17, v215
	v_cmp_ge_u32_e32 vcc, v216, v218
	v_cndmask_b32_e32 v7, v217, v7, vcc
	v_mul_f32_e32 v8, 0x3db504f3, v8
	v_add_u32_e32 v218, 18, v215
	v_cmp_ge_u32_e32 vcc, v216, v218
	v_cndmask_b32_e32 v8, v217, v8, vcc
	v_mul_f32_e32 v9, 0x3db504f3, v9
	v_add_u32_e32 v218, 19, v215
	v_cmp_ge_u32_e32 vcc, v216, v218
	v_cndmask_b32_e32 v9, v217, v9, vcc
	v_mul_f32_e32 v10, 0x3db504f3, v10
	v_add_u32_e32 v218, 32, v215
	v_cmp_ge_u32_e32 vcc, v216, v218
	v_cndmask_b32_e32 v10, v217, v10, vcc
	v_mul_f32_e32 v11, 0x3db504f3, v11
	v_add_u32_e32 v218, 33, v215
	v_cmp_ge_u32_e32 vcc, v216, v218
	v_cndmask_b32_e32 v11, v217, v11, vcc
	v_mul_f32_e32 v12, 0x3db504f3, v12
	v_add_u32_e32 v218, 34, v215
	v_cmp_ge_u32_e32 vcc, v216, v218
	v_cndmask_b32_e32 v12, v217, v12, vcc
	v_mul_f32_e32 v13, 0x3db504f3, v13
	v_add_u32_e32 v218, 35, v215
	v_cmp_ge_u32_e32 vcc, v216, v218
	v_cndmask_b32_e32 v13, v217, v13, vcc
	v_mul_f32_e32 v14, 0x3db504f3, v14
	v_add_u32_e32 v218, 48, v215
	v_cmp_ge_u32_e32 vcc, v216, v218
	v_cndmask_b32_e32 v14, v217, v14, vcc
	v_mul_f32_e32 v15, 0x3db504f3, v15
	v_add_u32_e32 v218, 49, v215
	v_cmp_ge_u32_e32 vcc, v216, v218
	v_cndmask_b32_e32 v15, v217, v15, vcc
	v_mul_f32_e32 v16, 0x3db504f3, v16
	v_add_u32_e32 v218, 50, v215
	v_cmp_ge_u32_e32 vcc, v216, v218
	v_cndmask_b32_e32 v16, v217, v16, vcc
	v_mul_f32_e32 v17, 0x3db504f3, v17
	v_add_u32_e32 v218, 51, v215
	v_cmp_ge_u32_e32 vcc, v216, v218
	v_cndmask_b32_e32 v17, v217, v17, vcc
	v_mul_f32_e32 v18, 0x3db504f3, v18
	v_add_u32_e32 v218, 64, v215
	v_cmp_ge_u32_e32 vcc, v216, v218
	v_cndmask_b32_e32 v18, v217, v18, vcc
	v_mul_f32_e32 v19, 0x3db504f3, v19
	v_add_u32_e32 v218, 65, v215
	v_cmp_ge_u32_e32 vcc, v216, v218
	v_cndmask_b32_e32 v19, v217, v19, vcc
	v_mul_f32_e32 v20, 0x3db504f3, v20
	v_add_u32_e32 v218, 66, v215
	v_cmp_ge_u32_e32 vcc, v216, v218
	v_cndmask_b32_e32 v20, v217, v20, vcc
	v_mul_f32_e32 v21, 0x3db504f3, v21
	v_add_u32_e32 v218, 67, v215
	v_cmp_ge_u32_e32 vcc, v216, v218
	v_cndmask_b32_e32 v21, v217, v21, vcc
	v_mul_f32_e32 v22, 0x3db504f3, v22
	v_add_u32_e32 v218, 80, v215
	v_cmp_ge_u32_e32 vcc, v216, v218
	v_cndmask_b32_e32 v22, v217, v22, vcc
	v_mul_f32_e32 v23, 0x3db504f3, v23
	v_add_u32_e32 v218, 81, v215
	v_cmp_ge_u32_e32 vcc, v216, v218
	v_cndmask_b32_e32 v23, v217, v23, vcc
	v_mul_f32_e32 v24, 0x3db504f3, v24
	v_add_u32_e32 v218, 82, v215
	v_cmp_ge_u32_e32 vcc, v216, v218
	v_cndmask_b32_e32 v24, v217, v24, vcc
	v_mul_f32_e32 v25, 0x3db504f3, v25
	v_add_u32_e32 v218, 83, v215
	v_cmp_ge_u32_e32 vcc, v216, v218
	v_cndmask_b32_e32 v25, v217, v25, vcc
	v_mul_f32_e32 v26, 0x3db504f3, v26
	v_add_u32_e32 v218, 96, v215
	v_cmp_ge_u32_e32 vcc, v216, v218
	v_cndmask_b32_e32 v26, v217, v26, vcc
	v_mul_f32_e32 v27, 0x3db504f3, v27
	v_add_u32_e32 v218, 97, v215
	v_cmp_ge_u32_e32 vcc, v216, v218
	v_cndmask_b32_e32 v27, v217, v27, vcc
	v_mul_f32_e32 v28, 0x3db504f3, v28
	v_add_u32_e32 v218, 98, v215
	v_cmp_ge_u32_e32 vcc, v216, v218
	v_cndmask_b32_e32 v28, v217, v28, vcc
	v_mul_f32_e32 v29, 0x3db504f3, v29
	v_add_u32_e32 v218, 99, v215
	v_cmp_ge_u32_e32 vcc, v216, v218
	v_cndmask_b32_e32 v29, v217, v29, vcc
	v_mul_f32_e32 v30, 0x3db504f3, v30
	v_add_u32_e32 v218, 112, v215
	v_cmp_ge_u32_e32 vcc, v216, v218
	v_cndmask_b32_e32 v30, v217, v30, vcc
	v_mul_f32_e32 v31, 0x3db504f3, v31
	v_add_u32_e32 v218, 113, v215
	v_cmp_ge_u32_e32 vcc, v216, v218
	v_cndmask_b32_e32 v31, v217, v31, vcc
	v_mul_f32_e32 v32, 0x3db504f3, v32
	v_add_u32_e32 v218, 114, v215
	v_cmp_ge_u32_e32 vcc, v216, v218
	v_cndmask_b32_e32 v32, v217, v32, vcc
	v_mul_f32_e32 v33, 0x3db504f3, v33
	v_add_u32_e32 v218, 115, v215
	v_cmp_ge_u32_e32 vcc, v216, v218
	v_cndmask_b32_e32 v33, v217, v33, vcc
	v_mul_f32_e32 v34, 0x3db504f3, v34
	v_add_u32_e32 v218, 128, v215
	v_cmp_ge_u32_e32 vcc, v216, v218
	v_cndmask_b32_e32 v34, v217, v34, vcc
	v_mul_f32_e32 v35, 0x3db504f3, v35
	v_add_u32_e32 v218, 129, v215
	v_cmp_ge_u32_e32 vcc, v216, v218
	v_cndmask_b32_e32 v35, v217, v35, vcc
	v_mul_f32_e32 v36, 0x3db504f3, v36
	v_add_u32_e32 v218, 130, v215
	v_cmp_ge_u32_e32 vcc, v216, v218
	v_cndmask_b32_e32 v36, v217, v36, vcc
	v_mul_f32_e32 v37, 0x3db504f3, v37
	v_add_u32_e32 v218, 131, v215
	v_cmp_ge_u32_e32 vcc, v216, v218
	v_cndmask_b32_e32 v37, v217, v37, vcc
	v_mul_f32_e32 v38, 0x3db504f3, v38
	v_add_u32_e32 v218, 144, v215
	v_cmp_ge_u32_e32 vcc, v216, v218
	v_cndmask_b32_e32 v38, v217, v38, vcc
	v_mul_f32_e32 v39, 0x3db504f3, v39
	v_add_u32_e32 v218, 145, v215
	v_cmp_ge_u32_e32 vcc, v216, v218
	v_cndmask_b32_e32 v39, v217, v39, vcc
	v_mul_f32_e32 v40, 0x3db504f3, v40
	v_add_u32_e32 v218, 146, v215
	v_cmp_ge_u32_e32 vcc, v216, v218
	v_cndmask_b32_e32 v40, v217, v40, vcc
	v_mul_f32_e32 v41, 0x3db504f3, v41
	v_add_u32_e32 v218, 147, v215
	v_cmp_ge_u32_e32 vcc, v216, v218
	v_cndmask_b32_e32 v41, v217, v41, vcc
	v_max_f32_e32 v225, v2, v3
	v_max3_f32 v225, v225, v4, v5
	v_max3_f32 v225, v225, v6, v7
	v_max3_f32 v225, v225, v8, v9
	v_max3_f32 v225, v225, v10, v11
	v_max3_f32 v225, v225, v12, v13
	v_max3_f32 v225, v225, v14, v15
	v_max3_f32 v225, v225, v16, v17
	v_max3_f32 v225, v225, v18, v19
	v_max3_f32 v225, v225, v20, v21
	v_max3_f32 v225, v225, v22, v23
	v_max3_f32 v225, v225, v24, v25
	v_max3_f32 v225, v225, v26, v27
	v_max3_f32 v225, v225, v28, v29
	v_max3_f32 v225, v225, v30, v31
	v_max3_f32 v225, v225, v32, v33
	v_max3_f32 v225, v225, v34, v35
	v_max3_f32 v225, v225, v36, v37
	v_max3_f32 v225, v225, v38, v39
	v_max3_f32 v225, v225, v40, v41
	ds_bpermute_b32 v218, v191, v225
	s_waitcnt lgkmcnt(0)
; DI unsigned pk2(float lo, float hi) { const bf2_t r = __builtin_convertvector((f32x2_t){lo, hi}, bf2_t); return __builtin_bit_cast(unsigned, r); }
; #define DSEC(k) do { if (PROBE_DSEC) { const unsigned long long tn_ = __builtin_amdgcn_s_memrealtime(); if (PROBE_DSEC == (k)) tsec += tn_ - tl_; tl_ = tn_; } } while (0)
; DI void dil_attn_phase(LAS unsigned char* L, const bf16* Z, const float* cosT, const float* sinT, bf16* OG, float* LSE, int G, int bid, int tid, unsigned long long& tsec) {
;     ...
;         mx = fmaxf(mx, __shfl_xor(mx, 16)); mx = fmaxf(mx, __shfl_xor(mx, 32));
;         float den = 0.f;
; #pragma unroll
;         for (int tix = 0; tix < 10; ++tix)
; #pragma unroll
;             for (int e = 0; e < 4; ++e) { const float p = __expf(s[tix][e] - mx); s[tix][e] = p; den += p; }
;         den += __shfl_xor(den, 16); den += __shfl_xor(den, 32);
;         DSEC(5);
;         bf16x8 pf[5];
; #pragma unroll
;         for (int pp = 0; pp < 5; ++pp) { u32x4 pw; pw.x = pk2(s[2 * pp][0], s[2 * pp][1]); pw.y = pk2(s[2 * pp][2], s[2 * pp][3]); pw.z = pk2(s[2 * pp + 1][0], s[2 * pp + 1][1]); pw.w = pk2(s[2 * pp + 1][2], s[2 * pp + 1][3]); pf[pp] = mk8(pw); }
	v_max_f32_e32 v218, v218, v218
	v_max_f32_e32 v225, v225, v218
	ds_bpermute_b32 v218, v192, v225
	s_waitcnt lgkmcnt(0)
	v_max_f32_e32 v218, v218, v218
	v_max_f32_e32 v225, v225, v218
	v_sub_f32_e32 v2, v2, v225
	v_sub_f32_e32 v3, v3, v225
	v_sub_f32_e32 v4, v4, v225
	v_sub_f32_e32 v5, v5, v225
	v_sub_f32_e32 v6, v6, v225
	v_sub_f32_e32 v7, v7, v225
	v_sub_f32_e32 v8, v8, v225
	v_sub_f32_e32 v9, v9, v225
	v_sub_f32_e32 v10, v10, v225
	v_sub_f32_e32 v11, v11, v225
	v_sub_f32_e32 v12, v12, v225
	v_sub_f32_e32 v13, v13, v225
	v_sub_f32_e32 v14, v14, v225
	v_sub_f32_e32 v15, v15, v225
	v_sub_f32_e32 v16, v16, v225
	v_sub_f32_e32 v17, v17, v225
	v_sub_f32_e32 v18, v18, v225
	v_sub_f32_e32 v19, v19, v225
	v_sub_f32_e32 v20, v20, v225
	v_sub_f32_e32 v21, v21, v225
	v_sub_f32_e32 v22, v22, v225
	v_sub_f32_e32 v23, v23, v225
	v_sub_f32_e32 v24, v24, v225
	v_sub_f32_e32 v25, v25, v225
	v_sub_f32_e32 v26, v26, v225
	v_sub_f32_e32 v27, v27, v225
	v_sub_f32_e32 v28, v28, v225
	v_sub_f32_e32 v29, v29, v225
	v_sub_f32_e32 v30, v30, v225
	v_sub_f32_e32 v31, v31, v225
	v_sub_f32_e32 v32, v32, v225
	v_sub_f32_e32 v33, v33, v225
	v_sub_f32_e32 v34, v34, v225
	v_sub_f32_e32 v35, v35, v225
	v_sub_f32_e32 v36, v36, v225
	v_sub_f32_e32 v37, v37, v225
	v_sub_f32_e32 v38, v38, v225
	v_sub_f32_e32 v39, v39, v225
	v_sub_f32_e32 v40, v40, v225
	v_sub_f32_e32 v41, v41, v225
	v_mul_f32_e32 v2, 0x3fb8aa3b, v2
	v_mul_f32_e32 v3, 0x3fb8aa3b, v3
	v_mul_f32_e32 v4, 0x3fb8aa3b, v4
	v_mul_f32_e32 v5, 0x3fb8aa3b, v5
	v_mul_f32_e32 v6, 0x3fb8aa3b, v6
	v_mul_f32_e32 v7, 0x3fb8aa3b, v7
	v_mul_f32_e32 v8, 0x3fb8aa3b, v8
	v_mul_f32_e32 v9, 0x3fb8aa3b, v9
	v_mul_f32_e32 v10, 0x3fb8aa3b, v10
	v_mul_f32_e32 v11, 0x3fb8aa3b, v11
	v_mul_f32_e32 v12, 0x3fb8aa3b, v12
	v_mul_f32_e32 v13, 0x3fb8aa3b, v13
	v_mul_f32_e32 v14, 0x3fb8aa3b, v14
	v_mul_f32_e32 v15, 0x3fb8aa3b, v15
	v_mul_f32_e32 v16, 0x3fb8aa3b, v16
	v_mul_f32_e32 v17, 0x3fb8aa3b, v17
	v_mul_f32_e32 v18, 0x3fb8aa3b, v18
	v_mul_f32_e32 v19, 0x3fb8aa3b, v19
	v_mul_f32_e32 v20, 0x3fb8aa3b, v20
	v_mul_f32_e32 v21, 0x3fb8aa3b, v21
	v_mul_f32_e32 v22, 0x3fb8aa3b, v22
	v_mul_f32_e32 v23, 0x3fb8aa3b, v23
	v_mul_f32_e32 v24, 0x3fb8aa3b, v24
	v_mul_f32_e32 v25, 0x3fb8aa3b, v25
	v_mul_f32_e32 v26, 0x3fb8aa3b, v26
	v_mul_f32_e32 v27, 0x3fb8aa3b, v27
	v_mul_f32_e32 v28, 0x3fb8aa3b, v28
	v_mul_f32_e32 v29, 0x3fb8aa3b, v29
	v_mul_f32_e32 v30, 0x3fb8aa3b, v30
	v_mul_f32_e32 v31, 0x3fb8aa3b, v31
	v_mul_f32_e32 v32, 0x3fb8aa3b, v32
	v_mul_f32_e32 v33, 0x3fb8aa3b, v33
	v_mul_f32_e32 v34, 0x3fb8aa3b, v34
	v_mul_f32_e32 v35, 0x3fb8aa3b, v35
	v_mul_f32_e32 v36, 0x3fb8aa3b, v36
	v_mul_f32_e32 v37, 0x3fb8aa3b, v37
	v_mul_f32_e32 v38, 0x3fb8aa3b, v38
	v_mul_f32_e32 v39, 0x3fb8aa3b, v39
	v_mul_f32_e32 v40, 0x3fb8aa3b, v40
	v_mul_f32_e32 v41, 0x3fb8aa3b, v41
	v_exp_f32_e32 v2, v2
	v_exp_f32_e32 v3, v3
	v_exp_f32_e32 v4, v4
	v_exp_f32_e32 v5, v5
	v_exp_f32_e32 v6, v6
	v_exp_f32_e32 v7, v7
	v_exp_f32_e32 v8, v8
	v_exp_f32_e32 v9, v9
	v_exp_f32_e32 v10, v10
	v_exp_f32_e32 v11, v11
	v_exp_f32_e32 v12, v12
	v_exp_f32_e32 v13, v13
	v_exp_f32_e32 v14, v14
	v_exp_f32_e32 v15, v15
	v_exp_f32_e32 v16, v16
	v_exp_f32_e32 v17, v17
	v_exp_f32_e32 v18, v18
	v_exp_f32_e32 v19, v19
	v_exp_f32_e32 v20, v20
	v_exp_f32_e32 v21, v21
	v_exp_f32_e32 v22, v22
	v_exp_f32_e32 v23, v23
	v_exp_f32_e32 v24, v24
	v_exp_f32_e32 v25, v25
	v_exp_f32_e32 v26, v26
	v_exp_f32_e32 v27, v27
	v_exp_f32_e32 v28, v28
	v_exp_f32_e32 v29, v29
	v_exp_f32_e32 v30, v30
	v_exp_f32_e32 v31, v31
	v_exp_f32_e32 v32, v32
	v_exp_f32_e32 v33, v33
	v_exp_f32_e32 v34, v34
	v_exp_f32_e32 v35, v35
	v_exp_f32_e32 v36, v36
	v_exp_f32_e32 v37, v37
	v_exp_f32_e32 v38, v38
	v_exp_f32_e32 v39, v39
	v_exp_f32_e32 v40, v40
	v_exp_f32_e32 v41, v41
	s_nop 0
	v_add_f32_e32 v226, 0, v2
	v_add_f32_e32 v226, v3, v226
	v_add_f32_e32 v226, v4, v226
	v_add_f32_e32 v226, v5, v226
	v_add_f32_e32 v226, v6, v226
	v_add_f32_e32 v226, v7, v226
	v_add_f32_e32 v226, v8, v226
	v_add_f32_e32 v226, v9, v226
	v_add_f32_e32 v226, v10, v226
	v_add_f32_e32 v226, v11, v226
	v_add_f32_e32 v226, v12, v226
	v_add_f32_e32 v226, v13, v226
	v_add_f32_e32 v226, v14, v226
	v_add_f32_e32 v226, v15, v226
	v_add_f32_e32 v226, v16, v226
	v_add_f32_e32 v226, v17, v226
	v_add_f32_e32 v226, v18, v226
	v_add_f32_e32 v226, v19, v226
	v_add_f32_e32 v226, v20, v226
	v_add_f32_e32 v226, v21, v226
	v_add_f32_e32 v226, v22, v226
	v_add_f32_e32 v226, v23, v226
	v_add_f32_e32 v226, v24, v226
	v_add_f32_e32 v226, v25, v226
	v_add_f32_e32 v226, v26, v226
	v_add_f32_e32 v226, v27, v226
	v_add_f32_e32 v226, v28, v226
	v_add_f32_e32 v226, v29, v226
	v_add_f32_e32 v226, v30, v226
	v_add_f32_e32 v226, v31, v226
	v_add_f32_e32 v226, v32, v226
	v_add_f32_e32 v226, v33, v226
	v_add_f32_e32 v226, v34, v226
	v_add_f32_e32 v226, v35, v226
	v_add_f32_e32 v226, v36, v226
	v_add_f32_e32 v226, v37, v226
	v_add_f32_e32 v226, v38, v226
	v_add_f32_e32 v226, v39, v226
	v_add_f32_e32 v226, v40, v226
	v_add_f32_e32 v226, v41, v226
	ds_bpermute_b32 v218, v191, v226
	s_waitcnt lgkmcnt(0)
	v_add_f32_e32 v226, v226, v218
	ds_bpermute_b32 v218, v192, v226
	s_waitcnt lgkmcnt(0)
	v_add_f32_e32 v226, v226, v218
	v_rcp_f32_e32 v224, v226
	v_cvt_pk_bf16_f32 v122, v2, v3
	v_cvt_pk_bf16_f32 v123, v4, v5
	v_cvt_pk_bf16_f32 v124, v6, v7
	v_cvt_pk_bf16_f32 v125, v8, v9
	v_cvt_pk_bf16_f32 v126, v10, v11
	v_cvt_pk_bf16_f32 v127, v12, v13
	v_cvt_pk_bf16_f32 v128, v14, v15
	v_cvt_pk_bf16_f32 v129, v16, v17
	v_cvt_pk_bf16_f32 v130, v18, v19
	v_cvt_pk_bf16_f32 v131, v20, v21
	v_cvt_pk_bf16_f32 v132, v22, v23
	v_cvt_pk_bf16_f32 v133, v24, v25
	v_cvt_pk_bf16_f32 v134, v26, v27
	v_cvt_pk_bf16_f32 v135, v28, v29
	v_cvt_pk_bf16_f32 v136, v30, v31
	v_cvt_pk_bf16_f32 v137, v32, v33
	v_cvt_pk_bf16_f32 v138, v34, v35
	v_cvt_pk_bf16_f32 v139, v36, v37
	v_cvt_pk_bf16_f32 v140, v38, v39
	v_cvt_pk_bf16_f32 v141, v40, v41
	s_waitcnt vmcnt(12)
	s_barrier
; #define LAS __attribute__((address_space(3)))
; #define MFMA16(a, b, c) __builtin_amdgcn_mfma_f32_16x16x32_bf16((a), (b), (c), 0, 0, 0)
; DI void dil_attn_phase(LAS unsigned char* L, const bf16* Z, const float* cosT, const float* sinT, bf16* OG, float* LSE, int G, int bid, int tid, unsigned long long& tsec) {
;     ...
; #pragma unroll
;         for (int pp = 0; pp < 5; ++pp)
; #pragma unroll
;             for (int d4 = 0; d4 < 2; ++d4) { bf16x8 vf[4];
; #pragma unroll
;                 for (int dq = 0; dq < 4; ++dq) { const int dt = 4 * d4 + dq; const LAS unsigned char* vb_ = ((dt & 1) ? vod : vev) + 16 * dt * VSTR + 64 * pp;
;                     const s16x4 lo = *(const LAS s16x4*)(vb_ + (((2 * dt) & 4) << 3)), hi = *(const LAS s16x4*)(vb_ + ((((2 * dt) & 4) ^ 4) << 3)); vf[dq] = __builtin_shufflevector(lo, hi, 0, 1, 2, 3, 4, 5, 6, 7); }
; #pragma unroll
;                 for (int dq = 0; dq < 4; ++dq) o[4 * d4 + dq] = MFMA16(vf[dq], pf[pp], o[4 * d4 + dq]);
;             }
	ds_read_b64_tr_b16 v[58:59], v178 offset:0
	ds_read_b64_tr_b16 v[60:61], v178 offset:4096
	ds_read_b64_tr_b16 v[62:63], v179 offset:0
	ds_read_b64_tr_b16 v[64:65], v179 offset:4096
	ds_read_b64_tr_b16 v[66:67], v180 offset:0
	ds_read_b64_tr_b16 v[68:69], v180 offset:4096
	ds_read_b64_tr_b16 v[70:71], v181 offset:0
	ds_read_b64_tr_b16 v[72:73], v181 offset:4096
	ds_read_b64_tr_b16 v[74:75], v182 offset:0
	ds_read_b64_tr_b16 v[76:77], v182 offset:4096
	ds_read_b64_tr_b16 v[78:79], v183 offset:0
	ds_read_b64_tr_b16 v[80:81], v183 offset:4096
	ds_read_b64_tr_b16 v[82:83], v184 offset:0
	ds_read_b64_tr_b16 v[84:85], v184 offset:4096
	ds_read_b64_tr_b16 v[86:87], v185 offset:0
	ds_read_b64_tr_b16 v[88:89], v185 offset:4096
	ds_read_b64_tr_b16 v[90:91], v178 offset:8192
	ds_read_b64_tr_b16 v[92:93], v178 offset:12288
	ds_read_b64_tr_b16 v[94:95], v179 offset:8192
	ds_read_b64_tr_b16 v[96:97], v179 offset:12288
	ds_read_b64_tr_b16 v[98:99], v180 offset:8192
	ds_read_b64_tr_b16 v[100:101], v180 offset:12288
	ds_read_b64_tr_b16 v[102:103], v181 offset:8192
	ds_read_b64_tr_b16 v[104:105], v181 offset:12288
	ds_read_b64_tr_b16 v[106:107], v182 offset:8192
	ds_read_b64_tr_b16 v[108:109], v182 offset:12288
	ds_read_b64_tr_b16 v[110:111], v183 offset:8192
	ds_read_b64_tr_b16 v[112:113], v183 offset:12288
	ds_read_b64_tr_b16 v[114:115], v184 offset:8192
	ds_read_b64_tr_b16 v[116:117], v184 offset:12288
	ds_read_b64_tr_b16 v[118:119], v185 offset:8192
	ds_read_b64_tr_b16 v[120:121], v185 offset:12288
	s_waitcnt lgkmcnt(15)
	v_mfma_f32_16x16x32_bf16 v[142:145], v[58:61], v[122:125], 0
	ds_read_b64_tr_b16 v[58:59], v178 offset:16384
	ds_read_b64_tr_b16 v[60:61], v178 offset:20480
	v_mfma_f32_16x16x32_bf16 v[146:149], v[62:65], v[122:125], 0
	ds_read_b64_tr_b16 v[62:63], v179 offset:16384
	ds_read_b64_tr_b16 v[64:65], v179 offset:20480
	v_mfma_f32_16x16x32_bf16 v[150:153], v[66:69], v[122:125], 0
	ds_read_b64_tr_b16 v[66:67], v180 offset:16384
	ds_read_b64_tr_b16 v[68:69], v180 offset:20480
	v_mfma_f32_16x16x32_bf16 v[154:157], v[70:73], v[122:125], 0
	ds_read_b64_tr_b16 v[70:71], v181 offset:16384
	ds_read_b64_tr_b16 v[72:73], v181 offset:20480
	v_mfma_f32_16x16x32_bf16 v[158:161], v[74:77], v[122:125], 0
	ds_read_b64_tr_b16 v[74:75], v182 offset:16384
	ds_read_b64_tr_b16 v[76:77], v182 offset:20480
	v_mfma_f32_16x16x32_bf16 v[162:165], v[78:81], v[122:125], 0
	ds_read_b64_tr_b16 v[78:79], v183 offset:16384
	ds_read_b64_tr_b16 v[80:81], v183 offset:20480
	v_mfma_f32_16x16x32_bf16 v[166:169], v[82:85], v[122:125], 0
	ds_read_b64_tr_b16 v[82:83], v184 offset:16384
	ds_read_b64_tr_b16 v[84:85], v184 offset:20480
	v_mfma_f32_16x16x32_bf16 v[170:173], v[86:89], v[122:125], 0
	ds_read_b64_tr_b16 v[86:87], v185 offset:16384
	ds_read_b64_tr_b16 v[88:89], v185 offset:20480
	s_waitcnt lgkmcnt(15)
	v_mfma_f32_16x16x32_bf16 v[142:145], v[90:93], v[126:129], v[142:145]
	ds_read_b64_tr_b16 v[90:91], v178 offset:24576
	ds_read_b64_tr_b16 v[92:93], v178 offset:28672
	v_mfma_f32_16x16x32_bf16 v[146:149], v[94:97], v[126:129], v[146:149]
	ds_read_b64_tr_b16 v[94:95], v179 offset:24576
	ds_read_b64_tr_b16 v[96:97], v179 offset:28672
	v_mfma_f32_16x16x32_bf16 v[150:153], v[98:101], v[126:129], v[150:153]
	ds_read_b64_tr_b16 v[98:99], v180 offset:24576
	ds_read_b64_tr_b16 v[100:101], v180 offset:28672
	v_mfma_f32_16x16x32_bf16 v[154:157], v[102:105], v[126:129], v[154:157]
	ds_read_b64_tr_b16 v[102:103], v181 offset:24576
	ds_read_b64_tr_b16 v[104:105], v181 offset:28672
	v_mfma_f32_16x16x32_bf16 v[158:161], v[106:109], v[126:129], v[158:161]
	ds_read_b64_tr_b16 v[106:107], v182 offset:24576
	ds_read_b64_tr_b16 v[108:109], v182 offset:28672
	v_mfma_f32_16x16x32_bf16 v[162:165], v[110:113], v[126:129], v[162:165]
	ds_read_b64_tr_b16 v[110:111], v183 offset:24576
	ds_read_b64_tr_b16 v[112:113], v183 offset:28672
	v_mfma_f32_16x16x32_bf16 v[166:169], v[114:117], v[126:129], v[166:169]
	ds_read_b64_tr_b16 v[114:115], v184 offset:24576
	ds_read_b64_tr_b16 v[116:117], v184 offset:28672
	v_mfma_f32_16x16x32_bf16 v[170:173], v[118:121], v[126:129], v[170:173]
	ds_read_b64_tr_b16 v[118:119], v185 offset:24576
	ds_read_b64_tr_b16 v[120:121], v185 offset:28672
	s_waitcnt lgkmcnt(15)
	v_mfma_f32_16x16x32_bf16 v[142:145], v[58:61], v[130:133], v[142:145]
	ds_read_b64_tr_b16 v[58:59], v178 offset:32768
	ds_read_b64_tr_b16 v[60:61], v178 offset:36864
	v_mfma_f32_16x16x32_bf16 v[146:149], v[62:65], v[130:133], v[146:149]
	ds_read_b64_tr_b16 v[62:63], v179 offset:32768
	ds_read_b64_tr_b16 v[64:65], v179 offset:36864
	v_mfma_f32_16x16x32_bf16 v[150:153], v[66:69], v[130:133], v[150:153]
	ds_read_b64_tr_b16 v[66:67], v180 offset:32768
	ds_read_b64_tr_b16 v[68:69], v180 offset:36864
	v_mfma_f32_16x16x32_bf16 v[154:157], v[70:73], v[130:133], v[154:157]
	ds_read_b64_tr_b16 v[70:71], v181 offset:32768
	ds_read_b64_tr_b16 v[72:73], v181 offset:36864
	v_mfma_f32_16x16x32_bf16 v[158:161], v[74:77], v[130:133], v[158:161]
	ds_read_b64_tr_b16 v[74:75], v182 offset:32768
	ds_read_b64_tr_b16 v[76:77], v182 offset:36864
	v_mfma_f32_16x16x32_bf16 v[162:165], v[78:81], v[130:133], v[162:165]
	ds_read_b64_tr_b16 v[78:79], v183 offset:32768
	ds_read_b64_tr_b16 v[80:81], v183 offset:36864
	v_mfma_f32_16x16x32_bf16 v[166:169], v[82:85], v[130:133], v[166:169]
	ds_read_b64_tr_b16 v[82:83], v184 offset:32768
	ds_read_b64_tr_b16 v[84:85], v184 offset:36864
	v_mfma_f32_16x16x32_bf16 v[170:173], v[86:89], v[130:133], v[170:173]
	ds_read_b64_tr_b16 v[86:87], v185 offset:32768
	ds_read_b64_tr_b16 v[88:89], v185 offset:36864
	s_waitcnt lgkmcnt(15)
	v_mfma_f32_16x16x32_bf16 v[142:145], v[90:93], v[134:137], v[142:145]
	v_mfma_f32_16x16x32_bf16 v[146:149], v[94:97], v[134:137], v[146:149]
	v_mfma_f32_16x16x32_bf16 v[150:153], v[98:101], v[134:137], v[150:153]
	v_mfma_f32_16x16x32_bf16 v[154:157], v[102:105], v[134:137], v[154:157]
	v_mfma_f32_16x16x32_bf16 v[158:161], v[106:109], v[134:137], v[158:161]
	v_mfma_f32_16x16x32_bf16 v[162:165], v[110:113], v[134:137], v[162:165]
	v_mfma_f32_16x16x32_bf16 v[166:169], v[114:117], v[134:137], v[166:169]
	v_mfma_f32_16x16x32_bf16 v[170:173], v[118:121], v[134:137], v[170:173]
	s_waitcnt lgkmcnt(0)
	v_mfma_f32_16x16x32_bf16 v[142:145], v[58:61], v[138:141], v[142:145]
	v_mfma_f32_16x16x32_bf16 v[146:149], v[62:65], v[138:141], v[146:149]
	v_mfma_f32_16x16x32_bf16 v[150:153], v[66:69], v[138:141], v[150:153]
	v_mfma_f32_16x16x32_bf16 v[154:157], v[70:73], v[138:141], v[154:157]
	v_mfma_f32_16x16x32_bf16 v[158:161], v[74:77], v[138:141], v[158:161]
	v_mfma_f32_16x16x32_bf16 v[162:165], v[78:81], v[138:141], v[162:165]
	v_mfma_f32_16x16x32_bf16 v[166:169], v[82:85], v[138:141], v[166:169]
	v_mfma_f32_16x16x32_bf16 v[170:173], v[86:89], v[138:141], v[170:173]
	s_barrier
; DI unsigned pk2(float lo, float hi) { const bf2_t r = __builtin_convertvector((f32x2_t){lo, hi}, bf2_t); return __builtin_bit_cast(unsigned, r); }
; DI void dil_attn_phase(LAS unsigned char* L, const bf16* Z, const float* cosT, const float* sinT, bf16* OG, float* LSE, int G, int bid, int tid, unsigned long long& tsec) {
;     ...
;     if (bid < 1536) DIL_LOAD(bid);
;     for (int unit = bid; unit < 1536; unit += G) {
;         const int j = unit & 31, h = (unit >> 5) & 3, gb = unit >> 7, g = gb % 3, b = gb / 3;
;         const int dsh = 2 * g, Lseg = T >> dsh;
;         const int p0 = 128 * j, r = p0 / Lseg, u0 = p0 & (Lseg - 1);
;         const int tokbase = b * T + r;
;         const int colq = g * 512 + h * 128;
;         asm volatile("" : "+v"(kreg[0]), "+v"(kreg[1]), "+v"(kreg[2]), "+v"(kreg[3]), "+v"(kreg[4]), "+v"(kreg[5]), "+v"(kreg[6]), "+v"(kreg[7]));
;         asm volatile("" : "+v"(vreg[0]), "+v"(vreg[1]), "+v"(vreg[2]), "+v"(vreg[3]), "+v"(vreg[4]), "+v"(vreg[5]), "+v"(vreg[6]), "+v"(vreg[7]));
;         const int qi = 16 * wid + fr; const size_t tq = (size_t)(tokbase + ((u0 + qi) << dsh));
;     ...
;         const float inv = __builtin_amdgcn_rcpf(den), lse = mx + __logf(den);
;         { bf16* op = OG + tq * 1536 + colq + 4 * fq;
; #pragma unroll
;           for (int dt = 0; dt < 8; ++dt) *(unsigned long long*)(op + 16 * dt) = (unsigned long long)pk2(o[dt][0] * inv, o[dt][1] * inv) | ((unsigned long long)pk2(o[dt][2] * inv, o[dt][3] * inv) << 32); }
;         if (lane < 16) LSE[tq * 12 + g * 4 + h] = lse;
	s_add_u32 s44, s52, 6144
	s_addc_u32 s45, s53, 0
	s_sub_u32 s23, s51, 0x80
	v_add_u32_e32 v218, 0, v193
	v_add_u32_e32 v218, s23, v218
	v_max_i32_e32 v218, 0, v218
	v_lshlrev_b32_e32 v218, s50, v218
	v_mul_u32_u24_e32 v218, 9, v218
	v_lshl_add_u32 v218, v218, 10, v206
	s_add_u32 m0, s40, 65536
	s_nop 0
	global_load_lds_dwordx4 v218, s[44:45]
	v_add_u32_e32 v218, 4, v193
	v_add_u32_e32 v218, s23, v218
	v_max_i32_e32 v218, 0, v218
	v_lshlrev_b32_e32 v218, s50, v218
	v_mul_u32_u24_e32 v218, 9, v218
	v_lshl_add_u32 v218, v218, 10, v207
	s_add_u32 m0, s40, 66560
	s_nop 0
	global_load_lds_dwordx4 v218, s[44:45]
	v_add_u32_e32 v218, 8, v193
	v_add_u32_e32 v218, s23, v218
	v_max_i32_e32 v218, 0, v218
	v_lshlrev_b32_e32 v218, s50, v218
	v_mul_u32_u24_e32 v218, 9, v218
	v_lshl_add_u32 v218, v218, 10, v208
	s_add_u32 m0, s40, 67584
	s_nop 0
	global_load_lds_dwordx4 v218, s[44:45]
	v_add_u32_e32 v218, 12, v193
	v_add_u32_e32 v218, s23, v218
	v_max_i32_e32 v218, 0, v218
	v_lshlrev_b32_e32 v218, s50, v218
	v_mul_u32_u24_e32 v218, 9, v218
	v_lshl_add_u32 v218, v218, 10, v209
	s_add_u32 m0, s40, 68608
	s_nop 0
	global_load_lds_dwordx4 v218, s[44:45]
	v_add_u32_e32 v218, 16, v193
	v_add_u32_e32 v218, s23, v218
	v_max_i32_e32 v218, 0, v218
	v_lshlrev_b32_e32 v218, s50, v218
	v_mul_u32_u24_e32 v218, 9, v218
	v_lshl_add_u32 v218, v218, 10, v206
	s_add_u32 m0, s40, 69632
	s_nop 0
	global_load_lds_dwordx4 v218, s[44:45]
	v_add_u32_e32 v218, 20, v193
	v_add_u32_e32 v218, s23, v218
	v_max_i32_e32 v218, 0, v218
	v_lshlrev_b32_e32 v218, s50, v218
	v_mul_u32_u24_e32 v218, 9, v218
	v_lshl_add_u32 v218, v218, 10, v207
	s_add_u32 m0, s40, 70656
	s_nop 0
	global_load_lds_dwordx4 v218, s[44:45]
	v_add_u32_e32 v218, 24, v193
	v_add_u32_e32 v218, s23, v218
	v_max_i32_e32 v218, 0, v218
	v_lshlrev_b32_e32 v218, s50, v218
	v_mul_u32_u24_e32 v218, 9, v218
	v_lshl_add_u32 v218, v218, 10, v208
	s_add_u32 m0, s40, 71680
	s_nop 0
	global_load_lds_dwordx4 v218, s[44:45]
	v_add_u32_e32 v218, 28, v193
	v_add_u32_e32 v218, s23, v218
	v_max_i32_e32 v218, 0, v218
	v_lshlrev_b32_e32 v218, s50, v218
	v_mul_u32_u24_e32 v218, 9, v218
	v_lshl_add_u32 v218, v218, 10, v209
	s_add_u32 m0, s40, 72704
	s_nop 0
	global_load_lds_dwordx4 v218, s[44:45]
	v_mul_f32_e32 v142, v224, v142
	v_mul_f32_e32 v143, v224, v143
	v_mul_f32_e32 v144, v224, v144
	v_mul_f32_e32 v145, v224, v145
	v_cvt_pk_bf16_f32 v142, v142, v143
	v_cvt_pk_bf16_f32 v143, v144, v145
	global_store_dwordx2 v213, v[142:143], s[14:15]
	v_mul_f32_e32 v146, v224, v146
	v_mul_f32_e32 v147, v224, v147
	v_mul_f32_e32 v148, v224, v148
	v_mul_f32_e32 v149, v224, v149
	v_cvt_pk_bf16_f32 v146, v146, v147
	v_cvt_pk_bf16_f32 v147, v148, v149
	global_store_dwordx2 v213, v[146:147], s[14:15] offset:32
	v_mul_f32_e32 v150, v224, v150
	v_mul_f32_e32 v151, v224, v151
	v_mul_f32_e32 v152, v224, v152
	v_mul_f32_e32 v153, v224, v153
	v_cvt_pk_bf16_f32 v150, v150, v151
	v_cvt_pk_bf16_f32 v151, v152, v153
	global_store_dwordx2 v213, v[150:151], s[14:15] offset:64
	v_mul_f32_e32 v154, v224, v154
	v_mul_f32_e32 v155, v224, v155
	v_mul_f32_e32 v156, v224, v156
	v_mul_f32_e32 v157, v224, v157
	v_cvt_pk_bf16_f32 v154, v154, v155
	v_cvt_pk_bf16_f32 v155, v156, v157
	global_store_dwordx2 v213, v[154:155], s[14:15] offset:96
	v_mul_f32_e32 v158, v224, v158
	v_mul_f32_e32 v159, v224, v159
	v_mul_f32_e32 v160, v224, v160
	v_mul_f32_e32 v161, v224, v161
	v_cvt_pk_bf16_f32 v158, v158, v159
	v_cvt_pk_bf16_f32 v159, v160, v161
	global_store_dwordx2 v213, v[158:159], s[14:15] offset:128
	v_mul_f32_e32 v162, v224, v162
	v_mul_f32_e32 v163, v224, v163
	v_mul_f32_e32 v164, v224, v164
	v_mul_f32_e32 v165, v224, v165
	v_cvt_pk_bf16_f32 v162, v162, v163
	v_cvt_pk_bf16_f32 v163, v164, v165
	global_store_dwordx2 v213, v[162:163], s[14:15] offset:160
	v_mul_f32_e32 v166, v224, v166
	v_mul_f32_e32 v167, v224, v167
	v_mul_f32_e32 v168, v224, v168
	v_mul_f32_e32 v169, v224, v169
	v_cvt_pk_bf16_f32 v166, v166, v167
	v_cvt_pk_bf16_f32 v167, v168, v169
	global_store_dwordx2 v213, v[166:167], s[14:15] offset:192
	v_mul_f32_e32 v170, v224, v170
	v_mul_f32_e32 v171, v224, v171
	v_mul_f32_e32 v172, v224, v172
	v_mul_f32_e32 v173, v224, v173
	v_cvt_pk_bf16_f32 v170, v170, v171
	v_cvt_pk_bf16_f32 v171, v172, v173
	global_store_dwordx2 v213, v[170:171], s[14:15] offset:224
	v_log_f32_e32 v218, v226
	s_nop 0
	v_mul_f32_e32 v219, 0x3f317217, v218
	v_fma_f32 v219, v218, s48, -v219
	v_fmac_f32_e32 v219, 0x3377d1cf, v218
	v_fmac_f32_e32 v219, 0x3f317217, v218
	v_add_f32_e32 v219, v225, v219
	v_cmp_eq_u32_e32 vcc, 0, v188
	s_and_saveexec_b64 s[54:55], vcc
	global_store_dword v214, v219, s[16:17]
	s_mov_b64 exec, s[54:55]
	s_add_u32 s23, s5, s22
	s_cmp_lt_u32 s23, 0x600
	s_cbranch_scc0 .Lda_done
	s_mov_b32 s5, s23
	s_and_b32 s41, s5, 31
	s_bfe_u32 s42, s5, 0x20005
	s_lshr_b32 s43, s5, 7
	s_mul_i32 s23, s43, 11
	s_lshr_b32 s23, s23, 5
	s_mul_i32 s25, s23, 3
	s_sub_u32 s25, s43, s25
	s_lshl_b32 s50, s25, 1
	s_lshl_b32 s26, s41, 7
	s_sub_u32 s27, 12, s50
	s_lshr_b32 s27, s26, s27
	s_lshr_b32 s51, 0xfff, s50
	s_and_b32 s51, s26, s51
	s_lshl_b32 s23, s23, 12
	s_add_u32 s23, s23, s27
	s_lshl_b32 s26, s25, 10
	s_lshl_b32 s27, s42, 8
	s_add_u32 s26, s26, s27
	s_mul_i32 s27, s23, 0x2400
	s_add_u32 s27, s27, s26
	s_add_u32 s52, s34, s27
	s_addc_u32 s53, s35, 0
	s_mov_b32 s18, s50
	s_mov_b32 s19, s51
	s_mul_i32 s27, s23, 0xc00
	s_add_u32 s27, s27, s26
	s_add_u32 s14, s36, s27
	s_addc_u32 s15, s37, 0
	s_mul_i32 s27, s23, 48
	s_lshl_b32 s26, s25, 4
	s_lshl_b32 s23, s42, 2
	s_add_u32 s26, s26, s23
	s_add_u32 s27, s27, s26
	s_add_u32 s16, s38, s27
	s_addc_u32 s17, s39, 0
	v_add_u32_e32 v218, s19, v189
	v_lshlrev_b32_e32 v218, s18, v218
	v_mul_u32_u24_e32 v219, 3, v218
	v_lshlrev_b32_e32 v219, 10, v219
	v_lshl_add_u32 v213, v188, 3, v219
	v_mul_u32_u24_e32 v214, 48, v218
	s_cmp_eq_u32 s19, 0
	s_cselect_b32 s23, 0x80, 0
	v_max_u32_e32 v219, s23, v189
	v_sub_u32_e32 v215, v190, v219
	v_sub_u32_e32 v216, v189, v219
	v_add_u32_e32 v216, 0x80, v216
	s_waitcnt vmcnt(17)
	s_barrier
	s_branch .Lda_loop
.Lda_done:
.LBB0_391:
	s_waitcnt vmcnt(0)
	s_barrier
	s_and_saveexec_b64 s[0:1], s[80:81]
	s_xor_b64 s[0:1], exec, s[0:1]
	s_cbranch_execz .LBB0_440
	v_readlane_b32 s2, v254, 25
	s_waitcnt vmcnt(0) expcnt(0) lgkmcnt(0)
	s_nop 0
	v_mov_b32_e32 v0, s2
	ds_read_b32 v3, v0
	v_readlane_b32 s2, v254, 26
	s_waitcnt lgkmcnt(0)
	v_cmp_ne_u32_e32 vcc, 0, v3
	v_mov_b32_e32 v0, s2
	ds_read_b32 v2, v0
	s_cbranch_vccnz .LBB0_407
	v_readlane_b32 s4, v252, 17
	v_readlane_b32 s5, v252, 18
	s_load_dwordx2 s[2:3], s[4:5], 0x4
	s_mov_b32 s9, 1
	s_waitcnt lgkmcnt(0)
	s_mul_i32 s8, s2, s29
	s_mul_i32 s8, s8, s3
	s_branch .LBB0_395
